# v31 + one static s_setprio 1 for waves 4-7 around the attention steady-state loop (strategy lever 4)
# speedup vs baseline: 1.0029x; 1.0029x over previous
; #define AT_LOAD(X, t) do { const size_t adv_ = (size_t)(t) * 64; sk##X = *(const u32x4*)(gk + adv_ * 1024); sv##X = *(const u32x4*)(gv + adv_ * 1024); if (rth) sr##X = *(const u32x4*)(gr + adv_ * 32); } while (0)
; #define AT_STORE(X, slot) do { *(LAS u32x4*)(lds + A_K0 + (slot) * AK_BYTES + lk) = sk##X; *(LAS u32x4*)(lds + A_V0 + (slot) * AV_BYTES + lv) = sv##X; if (rth) *(LAS u32x4*)(lds + A_K0 + (slot) * AK_BYTES + lr) = sr##X; } while (0)
; __device__ __forceinline__ void attn_unit(LAS char* lds, const bf16_t* Qp, const bf16_t* KVp, const bf16_t* KRp, int ntiles, bf16_t* Yp, bool dry) {
;     ...
;     for (int t = 0; t < ntiles; t += 2) {
;         const int sb0 = (t & 2);
;         const bool more = (t + 2 < ntiles);
;         f32x16 pa0 = {}, pa1 = {}, pb0 = {}, pb1 = {};
;         AT_QK(sb0, pa0, pa1);
;         AT_QK(sb0 + 1, pb0, pb1);
;         if (t == 0) AT_SMPV(sb0, true, pa0, pa1); else AT_SMPV(sb0, false, pa0, pa1);
;         __builtin_amdgcn_sched_barrier(0);
;         if (more) { AT_LOAD(A, t + 2); AT_LOAD(B, t + 3); }
;         AT_SMPV(sb0 + 1, false, pb0, pb1);
;         if (more) { AT_STORE(A, sb0 ^ 2); AT_STORE(B, (sb0 ^ 2) + 1); }
;         __syncthreads();
;     }
.Latt_iter:
	s_cmp_ge_u32 s29, 4
	s_cbranch_scc0 .Latt_prio_done
	s_setprio 1

; #define AT_LOAD(X, t) do { const size_t adv_ = (size_t)(t) * 64; sk##X = *(const u32x4*)(gk + adv_ * 1024); sv##X = *(const u32x4*)(gv + adv_ * 1024); if (rth) sr##X = *(const u32x4*)(gr + adv_ * 32); } while (0)
; #define AT_STORE(X, slot) do { *(LAS u32x4*)(lds + A_K0 + (slot) * AK_BYTES + lk) = sk##X; *(LAS u32x4*)(lds + A_V0 + (slot) * AV_BYTES + lv) = sv##X; if (rth) *(LAS u32x4*)(lds + A_K0 + (slot) * AK_BYTES + lr) = sr##X; } while (0)
; __device__ __forceinline__ void attn_unit(LAS char* lds, const bf16_t* Qp, const bf16_t* KVp, const bf16_t* KRp, int ntiles, bf16_t* Yp, bool dry) {
;     ...
;     for (int t = 0; t < ntiles; t += 2) {
;         const int sb0 = (t & 2);
;         const bool more = (t + 2 < ntiles);
;         f32x16 pa0 = {}, pa1 = {}, pb0 = {}, pb1 = {};
;         AT_QK(sb0, pa0, pa1);
;         AT_QK(sb0 + 1, pb0, pb1);
;         if (t == 0) AT_SMPV(sb0, true, pa0, pa1); else AT_SMPV(sb0, false, pa0, pa1);
;         __builtin_amdgcn_sched_barrier(0);
;         if (more) { AT_LOAD(A, t + 2); AT_LOAD(B, t + 3); }
;         AT_SMPV(sb0 + 1, false, pb0, pb1);
;         if (more) { AT_STORE(A, sb0 ^ 2); AT_STORE(B, (sb0 ^ 2) + 1); }
;         __syncthreads();
;     }
;     ...
;     lsum += __shfl_xor(lsum, 32);
.Latt_latch:
	s_add_i32 s35, s35, 2
	v_lshl_add_u64 v[192:193], v[192:193], 0, s[60:61]
	v_lshl_add_u64 v[194:195], v[194:195], 0, s[26:27]
	s_waitcnt lgkmcnt(0)
	s_barrier
	s_cmp_lt_u32 s35, 36
	s_cbranch_scc1 .Latt_loop
	v_and_b32_e32 v3, 64, v203
	v_xor_b32_e32 v2, 32, v203
	v_add_u32_e32 v3, 64, v3
	v_cmp_lt_i32_e32 vcc, v2, v3
	s_nop 1
	v_cndmask_b32_e32 v2, v203, v2, vcc
	v_lshlrev_b32_e32 v98, 2, v2
	s_setprio 0
	s_branch .LBB0_858
